# attention: next K/V tile staged into LDS mid exp-block (after 2nd MFMA group) instead of at tile end
# speedup vs baseline: 1.0040x; 1.0040x over previous
; template <int MODE> ...
;     ...
;   for (int it = 0; it < ntile; ++it) {
;     const int kt0 = (it < na) ? ka0 + it * 64 : kb0 + (it - na) * 64;
;     const bool masked = window && (it < na);
;     const u16* Ks = Kbase + (it & 1) * (2 * 64 * 64);
.Lattn1_adv:
	s_addk_i32 s2, 0x2000
	s_add_i32 s65, s65, 64
	s_cmp_lg_u32 s45, s66
	s_cbranch_scc1 .LBB0_875
	s_branch .LBB0_876

; #define MFMA(a, b, c) __builtin_amdgcn_mfma_f32_16x16x32_bf16((a), (b), (c), 0, 0, 0)
; template <int MODE> ...
;     ...
;     for (int kh = 0; kh < 2; ++kh) {
; #pragma unroll
;       for (int tt = 0; tt < 2; ++tt) {
;         bf16x8 pf[2];
; #pragma unroll
;         for (int hh = 0; hh < 2; ++hh) {
;           float pv[8];
; #pragma unroll
;           for (int j = 0; j < 4; ++j) {
;             pv[j] = __builtin_amdgcn_exp2f(S[kh][tt][hh][0][j]);
;             pv[4 + j] = __builtin_amdgcn_exp2f(S[kh][tt][hh][1][j]);
;           }
;           lsum[tt][hh] += ((pv[0] + pv[1]) + (pv[2] + pv[3])) + ((pv[4] + pv[5]) + (pv[6] + pv[7]));
;           const uint4 pk = make_uint4(pack2(pv[0], pv[1]), pack2(pv[2], pv[3]), pack2(pv[4], pv[5]), pack2(pv[6], pv[7]));
;           pf[hh] = __builtin_bit_cast(bf16x8, pk);
;         }
; #pragma unroll
;         for (int dt = 0; dt < 4; ++dt) {
;           const bf16x8 vf = *(const bf16x8*)&Vs[(dt * 16 + r) * 64 + (((kh * 4 + g) ^ (r & 7)) * 8)];
;           O[tt][0][dt] = MFMA(vf, pf[0], O[tt][0][dt]);
;           O[tt][1][dt] = MFMA(vf, pf[1], O[tt][1][dt]);
;         }
;       }
;     }
;     ...
;     if (more) {
;       u16* Kn = Kbase + ((it + 1) & 1) * (2 * 64 * 64);
;       *(uint4*)&Kn[kwoff] = kr0;
;       *(uint4*)&Kn[64 * 64 + vwoff] = vr0;
;     }
.LBB0_873:
	ds_read_b128 v[120:123], v234 offset:8192
	ds_read_b128 v[116:119], v234 offset:10240
	ds_read_b128 v[112:115], v234 offset:12288
	ds_read_b128 v[108:111], v234 offset:14336
	v_exp_f32_e32 v208, v192
	v_exp_f32_e32 v212, v193
	v_exp_f32_e32 v216, v190
	v_exp_f32_e32 v220, v191
	v_exp_f32_e32 v209, v202
	v_exp_f32_e32 v213, v203
	v_exp_f32_e32 v217, v200
	v_exp_f32_e32 v221, v201
	v_exp_f32_e32 v210, v198
	v_exp_f32_e32 v214, v199
	v_exp_f32_e32 v218, v196
	v_exp_f32_e32 v222, v197
	v_exp_f32_e32 v211, v206
	v_exp_f32_e32 v215, v207
	v_exp_f32_e32 v219, v204
	v_exp_f32_e32 v223, v205
	v_pk_add_f32 v[248:249], v[212:213], v[208:209]
	v_pk_add_f32 v[250:251], v[220:221], v[216:217]
	v_pk_add_f32 v[248:249], v[250:251], v[248:249]
	v_pk_add_f32 v[250:251], v[214:215], v[210:211]
	v_pk_add_f32 v[252:253], v[222:223], v[218:219]
	v_pk_add_f32 v[250:251], v[252:253], v[250:251]
	v_pk_add_f32 v[248:249], v[250:251], v[248:249]
	v_pk_add_f32 v[188:189], v[248:249], v[188:189]
	v_cvt_pk_bf16_f32 v240, v208, v212
	v_cvt_pk_bf16_f32 v241, v216, v220
	v_cvt_pk_bf16_f32 v242, v210, v214
	v_cvt_pk_bf16_f32 v243, v218, v222
	v_cvt_pk_bf16_f32 v244, v209, v213
	v_cvt_pk_bf16_f32 v245, v217, v221
	v_cvt_pk_bf16_f32 v246, v211, v215
	v_cvt_pk_bf16_f32 v247, v219, v223
	ds_read_b128 v[208:211], v0 offset:8192
	ds_read_b128 v[212:215], v0 offset:10240
	ds_read_b128 v[216:219], v0 offset:12288
	ds_read_b128 v[220:223], v0 offset:14336
	s_mov_b64 s[42:43], 0
	s_waitcnt lgkmcnt(4)
	v_mfma_f32_16x16x32_bf16 v[52:55], v[120:123], v[240:243], v[52:55]
	v_exp_f32_e32 v200, v129
	v_mfma_f32_16x16x32_bf16 v[60:63], v[116:119], v[240:243], v[60:63]
	v_exp_f32_e32 v196, v125
	v_mfma_f32_16x16x32_bf16 v[56:59], v[112:115], v[240:243], v[56:59]
	v_exp_f32_e32 v198, v126
	v_mfma_f32_16x16x32_bf16 v[64:67], v[108:111], v[240:243], v[64:67]
	v_exp_f32_e32 v206, v131
	v_mfma_f32_16x16x32_bf16 v[44:47], v[120:123], v[244:247], v[44:47]
	v_exp_f32_e32 v204, v127
	v_mfma_f32_16x16x32_bf16 v[40:43], v[116:119], v[244:247], v[40:43]
	v_exp_f32_e32 v193, v134
	v_mfma_f32_16x16x32_bf16 v[36:39], v[112:115], v[244:247], v[36:39]
	v_exp_f32_e32 v191, v138
	v_mfma_f32_16x16x32_bf16 v[48:51], v[108:111], v[244:247], v[48:51]
	v_exp_f32_e32 v201, v135
	v_exp_f32_e32 v197, v139
	v_exp_f32_e32 v203, v132
	v_exp_f32_e32 v207, v133
	v_exp_f32_e32 v205, v137
	v_exp_f32_e32 v192, v128
	v_exp_f32_e32 v190, v124
	v_exp_f32_e32 v202, v130
	v_exp_f32_e32 v199, v136
	v_pk_add_f32 v[248:249], v[200:201], v[192:193]
	v_pk_add_f32 v[250:251], v[206:207], v[202:203]
	v_pk_add_f32 v[248:249], v[250:251], v[248:249]
	v_pk_add_f32 v[250:251], v[196:197], v[190:191]
	v_pk_add_f32 v[252:253], v[204:205], v[198:199]
	v_pk_add_f32 v[250:251], v[252:253], v[250:251]
	v_pk_add_f32 v[248:249], v[250:251], v[248:249]
	v_pk_add_f32 v[186:187], v[248:249], v[186:187]
	v_cvt_pk_bf16_f32 v240, v192, v200
	v_cvt_pk_bf16_f32 v241, v202, v206
	v_cvt_pk_bf16_f32 v242, v190, v196
	v_cvt_pk_bf16_f32 v243, v198, v204
	v_cvt_pk_bf16_f32 v244, v193, v201
	v_cvt_pk_bf16_f32 v245, v203, v207
	v_cvt_pk_bf16_f32 v246, v191, v197
	v_cvt_pk_bf16_f32 v247, v199, v205
	v_mfma_f32_16x16x32_bf16 v[20:23], v[108:111], v[240:243], v[20:23]
	v_exp_f32_e32 v126, v168
	v_mfma_f32_16x16x32_bf16 v[32:35], v[120:123], v[240:243], v[32:35]
	v_exp_f32_e32 v132, v169
	v_mfma_f32_16x16x32_bf16 v[28:31], v[116:119], v[240:243], v[28:31]
	v_exp_f32_e32 v134, v170
	v_mfma_f32_16x16x32_bf16 v[24:27], v[112:115], v[240:243], v[24:27]
	v_exp_f32_e32 v138, v171
	v_mfma_f32_16x16x32_bf16 v[4:7], v[108:111], v[244:247], v[4:7]
	v_exp_f32_e32 v127, v142
	v_mfma_f32_16x16x32_bf16 v[16:19], v[120:123], v[244:247], v[16:19]
	v_exp_f32_e32 v125, v146
	v_mfma_f32_16x16x32_bf16 v[12:15], v[116:119], v[244:247], v[12:15]
	v_exp_f32_e32 v133, v143
	v_mfma_f32_16x16x32_bf16 v[8:11], v[112:115], v[244:247], v[8:11]
	v_exp_f32_e32 v129, v147
	s_andn2_b64 vcc, exec, s[56:57]
	s_cbranch_vccnz .Lattn1_nw
	s_and_b32 s98, s2, 0x2000
	s_lshl_b32 s98, s98, 1
	s_add_i32 s98, s98, 32
	v_lshl_add_u32 v235, v3, 1, s98
	v_lshl_add_u32 v238, v229, 1, s98
	s_waitcnt vmcnt(1)
	ds_write_b128 v235, v[100:103]
	s_waitcnt vmcnt(0)
	ds_write_b128 v238, v[104:107] offset:8192
; #define MFMA(a, b, c) __builtin_amdgcn_mfma_f32_16x16x32_bf16((a), (b), (c), 0, 0, 0)
; template <int MODE> ...
;     ...
;     for (int kh = 0; kh < 2; ++kh) {
; #pragma unroll
;       for (int tt = 0; tt < 2; ++tt) {
;         bf16x8 pf[2];
; #pragma unroll
;         for (int hh = 0; hh < 2; ++hh) {
;           float pv[8];
; #pragma unroll
;           for (int j = 0; j < 4; ++j) {
;             pv[j] = __builtin_amdgcn_exp2f(S[kh][tt][hh][0][j]);
;             pv[4 + j] = __builtin_amdgcn_exp2f(S[kh][tt][hh][1][j]);
;           }
;           lsum[tt][hh] += ((pv[0] + pv[1]) + (pv[2] + pv[3])) + ((pv[4] + pv[5]) + (pv[6] + pv[7]));
;           const uint4 pk = make_uint4(pack2(pv[0], pv[1]), pack2(pv[2], pv[3]), pack2(pv[4], pv[5]), pack2(pv[6], pv[7]));
;           pf[hh] = __builtin_bit_cast(bf16x8, pk);
;         }
; #pragma unroll
;         for (int dt = 0; dt < 4; ++dt) {
;           const bf16x8 vf = *(const bf16x8*)&Vs[(dt * 16 + r) * 64 + (((kh * 4 + g) ^ (r & 7)) * 8)];
;           O[tt][0][dt] = MFMA(vf, pf[0], O[tt][0][dt]);
;           O[tt][1][dt] = MFMA(vf, pf[1], O[tt][1][dt]);
;         }
;       }
;     }
.Lattn1_nw:
	v_exp_f32_e32 v135, v140
	v_exp_f32_e32 v131, v144
	v_exp_f32_e32 v139, v141
	v_exp_f32_e32 v137, v145
	v_exp_f32_e32 v124, v164
	v_exp_f32_e32 v128, v165
	v_exp_f32_e32 v130, v166
	v_exp_f32_e32 v136, v167
	v_pk_add_f32 v[248:249], v[132:133], v[126:127]
	v_pk_add_f32 v[250:251], v[138:139], v[134:135]
	v_pk_add_f32 v[248:249], v[250:251], v[248:249]
	v_pk_add_f32 v[250:251], v[128:129], v[124:125]
	v_pk_add_f32 v[252:253], v[136:137], v[130:131]
	v_pk_add_f32 v[250:251], v[252:253], v[250:251]
	v_pk_add_f32 v[248:249], v[250:251], v[248:249]
	v_pk_add_f32 v[188:189], v[248:249], v[188:189]
	v_cvt_pk_bf16_f32 v240, v126, v132
	v_cvt_pk_bf16_f32 v241, v134, v138
	v_cvt_pk_bf16_f32 v242, v124, v128
	v_cvt_pk_bf16_f32 v243, v130, v136
	v_cvt_pk_bf16_f32 v244, v127, v133
	v_cvt_pk_bf16_f32 v245, v135, v139
	v_cvt_pk_bf16_f32 v246, v125, v129
	v_cvt_pk_bf16_f32 v247, v131, v137
	s_waitcnt lgkmcnt(0)
	v_mfma_f32_16x16x32_bf16 v[52:55], v[208:211], v[240:243], v[52:55]
	v_exp_f32_e32 v148, v148
	v_mfma_f32_16x16x32_bf16 v[60:63], v[212:215], v[240:243], v[60:63]
	v_exp_f32_e32 v146, v152
	v_mfma_f32_16x16x32_bf16 v[56:59], v[216:219], v[240:243], v[56:59]
	v_exp_f32_e32 v152, v153
	v_mfma_f32_16x16x32_bf16 v[64:67], v[220:223], v[240:243], v[64:67]
	v_exp_f32_e32 v145, v163
	v_mfma_f32_16x16x32_bf16 v[44:47], v[208:211], v[244:247], v[44:47]
	v_exp_f32_e32 v141, v162
	v_mfma_f32_16x16x32_bf16 v[40:43], v[212:215], v[244:247], v[40:43]
	v_exp_f32_e32 v147, v160
	v_mfma_f32_16x16x32_bf16 v[36:39], v[216:219], v[244:247], v[36:39]
	v_exp_f32_e32 v153, v161
	v_mfma_f32_16x16x32_bf16 v[48:51], v[220:223], v[244:247], v[48:51]
	v_exp_f32_e32 v142, v150
	v_exp_f32_e32 v140, v154
	v_exp_f32_e32 v150, v151
	v_exp_f32_e32 v144, v155
	v_exp_f32_e32 v154, v149
	v_exp_f32_e32 v143, v158
	v_exp_f32_e32 v151, v159
	v_exp_f32_e32 v149, v156
	v_exp_f32_e32 v155, v157
	v_pk_add_f32 v[248:249], v[150:151], v[142:143]
	v_pk_add_f32 v[250:251], v[154:155], v[148:149]
	v_pk_add_f32 v[248:249], v[250:251], v[248:249]
	v_pk_add_f32 v[250:251], v[144:145], v[140:141]
	v_pk_add_f32 v[252:253], v[152:153], v[146:147]
	v_pk_add_f32 v[250:251], v[252:253], v[250:251]
	v_pk_add_f32 v[248:249], v[250:251], v[248:249]
	v_pk_add_f32 v[186:187], v[248:249], v[186:187]
	v_cvt_pk_bf16_f32 v240, v142, v150
	v_cvt_pk_bf16_f32 v241, v148, v154
	v_cvt_pk_bf16_f32 v242, v140, v144
	v_cvt_pk_bf16_f32 v243, v146, v152
	v_cvt_pk_bf16_f32 v244, v143, v151
	v_cvt_pk_bf16_f32 v245, v149, v155
	v_cvt_pk_bf16_f32 v246, v141, v145
	v_cvt_pk_bf16_f32 v247, v147, v153
	v_mfma_f32_16x16x32_bf16 v[32:35], v[208:211], v[240:243], v[32:35]
	v_mfma_f32_16x16x32_bf16 v[28:31], v[212:215], v[240:243], v[28:31]
	v_mfma_f32_16x16x32_bf16 v[24:27], v[216:219], v[240:243], v[24:27]
	v_mfma_f32_16x16x32_bf16 v[20:23], v[220:223], v[240:243], v[20:23]
	v_mfma_f32_16x16x32_bf16 v[16:19], v[208:211], v[244:247], v[16:19]
	v_mfma_f32_16x16x32_bf16 v[12:15], v[212:215], v[244:247], v[12:15]
	v_mfma_f32_16x16x32_bf16 v[8:11], v[216:219], v[244:247], v[8:11]
	v_mfma_f32_16x16x32_bf16 v[4:7], v[220:223], v[244:247], v[4:7]
	s_andn2_b64 vcc, exec, s[56:57]
	s_cbranch_vccz .Lattn1_adv

; template <int MODE> ...
;     ...
;   for (int it = 0; it < ntile; ++it) {
;     const int kt0 = (it < na) ? ka0 + it * 64 : kb0 + (it - na) * 64;
;     const bool masked = window && (it < na);
;     const u16* Ks = Kbase + (it & 1) * (2 * 64 * 64);
.Lattn2_adv:
	s_addk_i32 s2, 0x2000
	s_add_i32 s45, s45, 64
	s_cmp_lg_u32 s24, s54
	s_cbranch_scc1 .LBB0_895
	s_branch .LBB0_897

; #define MFMA(a, b, c) __builtin_amdgcn_mfma_f32_16x16x32_bf16((a), (b), (c), 0, 0, 0)
; template <int MODE> ...
;     ...
;     for (int kh = 0; kh < 2; ++kh) {
; #pragma unroll
;       for (int tt = 0; tt < 2; ++tt) {
;         bf16x8 pf[2];
; #pragma unroll
;         for (int hh = 0; hh < 2; ++hh) {
;           float pv[8];
; #pragma unroll
;           for (int j = 0; j < 4; ++j) {
;             pv[j] = __builtin_amdgcn_exp2f(S[kh][tt][hh][0][j]);
;             pv[4 + j] = __builtin_amdgcn_exp2f(S[kh][tt][hh][1][j]);
;           }
;           lsum[tt][hh] += ((pv[0] + pv[1]) + (pv[2] + pv[3])) + ((pv[4] + pv[5]) + (pv[6] + pv[7]));
;           const uint4 pk = make_uint4(pack2(pv[0], pv[1]), pack2(pv[2], pv[3]), pack2(pv[4], pv[5]), pack2(pv[6], pv[7]));
;           pf[hh] = __builtin_bit_cast(bf16x8, pk);
;         }
; #pragma unroll
;         for (int dt = 0; dt < 4; ++dt) {
;           const bf16x8 vf = *(const bf16x8*)&Vs[(dt * 16 + r) * 64 + (((kh * 4 + g) ^ (r & 7)) * 8)];
;           O[tt][0][dt] = MFMA(vf, pf[0], O[tt][0][dt]);
;           O[tt][1][dt] = MFMA(vf, pf[1], O[tt][1][dt]);
;         }
;       }
;     }
;     ...
;     if (more) {
;       u16* Kn = Kbase + ((it + 1) & 1) * (2 * 64 * 64);
;       *(uint4*)&Kn[kwoff] = kr0;
;       *(uint4*)&Kn[64 * 64 + vwoff] = vr0;
;     }
.LBB0_893:
	ds_read_b128 v[102:105], v198 offset:8192
	ds_read_b128 v[98:101], v198 offset:10240
	ds_read_b128 v[94:97], v198 offset:12288
	ds_read_b128 v[90:93], v198 offset:14336
	v_exp_f32_e32 v200, v176
	v_exp_f32_e32 v204, v177
	v_exp_f32_e32 v208, v174
	v_exp_f32_e32 v212, v175
	v_exp_f32_e32 v201, v184
	v_exp_f32_e32 v205, v185
	v_exp_f32_e32 v209, v182
	v_exp_f32_e32 v213, v183
	v_exp_f32_e32 v202, v180
	v_exp_f32_e32 v206, v181
	v_exp_f32_e32 v210, v178
	v_exp_f32_e32 v214, v179
	v_exp_f32_e32 v203, v188
	v_exp_f32_e32 v207, v189
	v_exp_f32_e32 v211, v186
	v_exp_f32_e32 v215, v187
	v_pk_add_f32 v[248:249], v[204:205], v[200:201]
	v_pk_add_f32 v[250:251], v[212:213], v[208:209]
	v_pk_add_f32 v[248:249], v[250:251], v[248:249]
	v_pk_add_f32 v[250:251], v[206:207], v[202:203]
	v_pk_add_f32 v[252:253], v[214:215], v[210:211]
	v_pk_add_f32 v[250:251], v[252:253], v[250:251]
	v_pk_add_f32 v[248:249], v[250:251], v[248:249]
	v_pk_add_f32 v[170:171], v[248:249], v[170:171]
	v_cvt_pk_bf16_f32 v240, v200, v204
	v_cvt_pk_bf16_f32 v241, v208, v212
	v_cvt_pk_bf16_f32 v242, v202, v206
	v_cvt_pk_bf16_f32 v243, v210, v214
	v_cvt_pk_bf16_f32 v244, v201, v205
	v_cvt_pk_bf16_f32 v245, v209, v213
	v_cvt_pk_bf16_f32 v246, v203, v207
	v_cvt_pk_bf16_f32 v247, v211, v215
	ds_read_b128 v[200:203], v197 offset:8192
	ds_read_b128 v[204:207], v197 offset:10240
	ds_read_b128 v[208:211], v197 offset:12288
	ds_read_b128 v[212:215], v197 offset:14336
	s_mov_b64 s[42:43], 0
	s_waitcnt lgkmcnt(4)
	v_mfma_f32_16x16x32_bf16 v[70:73], v[102:105], v[240:243], v[70:73]
	v_exp_f32_e32 v176, v114
	v_mfma_f32_16x16x32_bf16 v[78:81], v[98:101], v[240:243], v[78:81]
	v_exp_f32_e32 v182, v115
	v_mfma_f32_16x16x32_bf16 v[62:65], v[94:97], v[240:243], v[62:65]
	v_exp_f32_e32 v178, v107
	v_mfma_f32_16x16x32_bf16 v[74:77], v[90:93], v[240:243], v[74:77]
	v_exp_f32_e32 v184, v116
	v_mfma_f32_16x16x32_bf16 v[86:89], v[102:105], v[244:247], v[86:89]
	v_exp_f32_e32 v180, v108
	v_mfma_f32_16x16x32_bf16 v[66:69], v[98:101], v[244:247], v[66:69]
	v_exp_f32_e32 v188, v117
	v_mfma_f32_16x16x32_bf16 v[58:61], v[94:97], v[244:247], v[58:61]
	v_exp_f32_e32 v186, v109
	v_mfma_f32_16x16x32_bf16 v[82:85], v[90:93], v[244:247], v[82:85]
	v_exp_f32_e32 v175, v120
	v_exp_f32_e32 v183, v113
	v_exp_f32_e32 v179, v121
	v_exp_f32_e32 v189, v111
	v_exp_f32_e32 v187, v119
	v_exp_f32_e32 v174, v106
	v_exp_f32_e32 v177, v112
	v_exp_f32_e32 v185, v110
	v_exp_f32_e32 v181, v118
	v_pk_add_f32 v[248:249], v[182:183], v[176:177]
	v_pk_add_f32 v[250:251], v[188:189], v[184:185]
	v_pk_add_f32 v[248:249], v[250:251], v[248:249]
	v_pk_add_f32 v[250:251], v[178:179], v[174:175]
	v_pk_add_f32 v[252:253], v[186:187], v[180:181]
	v_pk_add_f32 v[250:251], v[252:253], v[250:251]
	v_pk_add_f32 v[248:249], v[250:251], v[248:249]
	v_pk_add_f32 v[156:157], v[248:249], v[156:157]
	v_cvt_pk_bf16_f32 v240, v176, v182
	v_cvt_pk_bf16_f32 v241, v184, v188
	v_cvt_pk_bf16_f32 v242, v174, v178
	v_cvt_pk_bf16_f32 v243, v180, v186
	v_cvt_pk_bf16_f32 v244, v177, v183
	v_cvt_pk_bf16_f32 v245, v185, v189
	v_cvt_pk_bf16_f32 v246, v175, v179
	v_cvt_pk_bf16_f32 v247, v181, v187
	v_mfma_f32_16x16x32_bf16 v[6:9], v[90:93], v[240:243], v[6:9]
	v_exp_f32_e32 v108, v150
	v_mfma_f32_16x16x32_bf16 v[42:45], v[102:105], v[240:243], v[42:45]
	v_exp_f32_e32 v114, v151
	v_mfma_f32_16x16x32_bf16 v[34:37], v[98:101], v[240:243], v[34:37]
	v_exp_f32_e32 v116, v152
	v_mfma_f32_16x16x32_bf16 v[10:13], v[94:97], v[240:243], v[10:13]
	v_exp_f32_e32 v120, v153
	v_mfma_f32_16x16x32_bf16 v[2:5], v[90:93], v[244:247], v[2:5]
	v_exp_f32_e32 v109, v124
	v_mfma_f32_16x16x32_bf16 v[46:49], v[102:105], v[244:247], v[46:49]
	v_exp_f32_e32 v107, v128
	v_mfma_f32_16x16x32_bf16 v[38:41], v[98:101], v[244:247], v[38:41]
	v_exp_f32_e32 v115, v125
	v_mfma_f32_16x16x32_bf16 v[14:17], v[94:97], v[244:247], v[14:17]
	v_exp_f32_e32 v111, v129
	s_andn2_b64 vcc, exec, s[48:49]
	s_cbranch_vccnz .Lattn2_nw
	s_and_b32 s98, s2, 0x2000
	s_lshl_b32 s98, s98, 1
	s_add_i32 s98, s98, 32
	v_lshl_add_u32 v235, v165, 1, s98
	v_lshl_add_u32 v238, v190, 1, s98
	s_waitcnt vmcnt(1)
	ds_write_b128 v235, v[50:53]
	s_waitcnt vmcnt(0)
	ds_write_b128 v238, v[54:57] offset:8192
; #define MFMA(a, b, c) __builtin_amdgcn_mfma_f32_16x16x32_bf16((a), (b), (c), 0, 0, 0)
; template <int MODE> ...
;     ...
;     for (int kh = 0; kh < 2; ++kh) {
; #pragma unroll
;       for (int tt = 0; tt < 2; ++tt) {
;         bf16x8 pf[2];
; #pragma unroll
;         for (int hh = 0; hh < 2; ++hh) {
;           float pv[8];
; #pragma unroll
;           for (int j = 0; j < 4; ++j) {
;             pv[j] = __builtin_amdgcn_exp2f(S[kh][tt][hh][0][j]);
;             pv[4 + j] = __builtin_amdgcn_exp2f(S[kh][tt][hh][1][j]);
;           }
;           lsum[tt][hh] += ((pv[0] + pv[1]) + (pv[2] + pv[3])) + ((pv[4] + pv[5]) + (pv[6] + pv[7]));
;           const uint4 pk = make_uint4(pack2(pv[0], pv[1]), pack2(pv[2], pv[3]), pack2(pv[4], pv[5]), pack2(pv[6], pv[7]));
;           pf[hh] = __builtin_bit_cast(bf16x8, pk);
;         }
; #pragma unroll
;         for (int dt = 0; dt < 4; ++dt) {
;           const bf16x8 vf = *(const bf16x8*)&Vs[(dt * 16 + r) * 64 + (((kh * 4 + g) ^ (r & 7)) * 8)];
;           O[tt][0][dt] = MFMA(vf, pf[0], O[tt][0][dt]);
;           O[tt][1][dt] = MFMA(vf, pf[1], O[tt][1][dt]);
;         }
;       }
;     }
.Lattn2_nw:
	v_exp_f32_e32 v117, v122
	v_exp_f32_e32 v113, v126
	v_exp_f32_e32 v121, v123
	v_exp_f32_e32 v119, v127
	v_exp_f32_e32 v106, v146
	v_exp_f32_e32 v110, v147
	v_exp_f32_e32 v112, v148
	v_exp_f32_e32 v118, v149
	v_pk_add_f32 v[248:249], v[114:115], v[108:109]
	v_pk_add_f32 v[250:251], v[120:121], v[116:117]
	v_pk_add_f32 v[248:249], v[250:251], v[248:249]
	v_pk_add_f32 v[250:251], v[110:111], v[106:107]
	v_pk_add_f32 v[252:253], v[118:119], v[112:113]
	v_pk_add_f32 v[250:251], v[252:253], v[250:251]
	v_pk_add_f32 v[248:249], v[250:251], v[248:249]
	v_pk_add_f32 v[170:171], v[248:249], v[170:171]
	v_cvt_pk_bf16_f32 v240, v108, v114
	v_cvt_pk_bf16_f32 v241, v116, v120
	v_cvt_pk_bf16_f32 v242, v106, v110
	v_cvt_pk_bf16_f32 v243, v112, v118
	v_cvt_pk_bf16_f32 v244, v109, v115
	v_cvt_pk_bf16_f32 v245, v117, v121
	v_cvt_pk_bf16_f32 v246, v107, v111
	v_cvt_pk_bf16_f32 v247, v113, v119
	s_waitcnt lgkmcnt(0)
	v_mfma_f32_16x16x32_bf16 v[70:73], v[200:203], v[240:243], v[70:73]
	v_exp_f32_e32 v130, v130
	v_mfma_f32_16x16x32_bf16 v[78:81], v[204:207], v[240:243], v[78:81]
	v_exp_f32_e32 v128, v134
	v_mfma_f32_16x16x32_bf16 v[62:65], v[208:211], v[240:243], v[62:65]
	v_exp_f32_e32 v134, v135
	v_mfma_f32_16x16x32_bf16 v[74:77], v[212:215], v[240:243], v[74:77]
	v_exp_f32_e32 v127, v145
	v_mfma_f32_16x16x32_bf16 v[86:89], v[200:203], v[244:247], v[86:89]
	v_exp_f32_e32 v123, v144
	v_mfma_f32_16x16x32_bf16 v[66:69], v[204:207], v[244:247], v[66:69]
	v_exp_f32_e32 v129, v142
	v_mfma_f32_16x16x32_bf16 v[58:61], v[208:211], v[244:247], v[58:61]
	v_exp_f32_e32 v135, v143
	v_mfma_f32_16x16x32_bf16 v[82:85], v[212:215], v[244:247], v[82:85]
	v_exp_f32_e32 v124, v132
	v_exp_f32_e32 v122, v136
	v_exp_f32_e32 v132, v133
	v_exp_f32_e32 v126, v137
	v_exp_f32_e32 v136, v131
	v_exp_f32_e32 v125, v140
	v_exp_f32_e32 v133, v141
	v_exp_f32_e32 v131, v138
	v_exp_f32_e32 v137, v139
	v_pk_add_f32 v[248:249], v[132:133], v[124:125]
	v_pk_add_f32 v[250:251], v[136:137], v[130:131]
	v_pk_add_f32 v[248:249], v[250:251], v[248:249]
	v_pk_add_f32 v[250:251], v[126:127], v[122:123]
	v_pk_add_f32 v[252:253], v[134:135], v[128:129]
	v_pk_add_f32 v[250:251], v[252:253], v[250:251]
	v_pk_add_f32 v[248:249], v[250:251], v[248:249]
	v_pk_add_f32 v[156:157], v[248:249], v[156:157]
	v_cvt_pk_bf16_f32 v240, v124, v132
	v_cvt_pk_bf16_f32 v241, v130, v136
	v_cvt_pk_bf16_f32 v242, v122, v126
	v_cvt_pk_bf16_f32 v243, v128, v134
	v_cvt_pk_bf16_f32 v244, v125, v133
	v_cvt_pk_bf16_f32 v245, v131, v137
	v_cvt_pk_bf16_f32 v246, v123, v127
	v_cvt_pk_bf16_f32 v247, v129, v135
	v_mfma_f32_16x16x32_bf16 v[42:45], v[200:203], v[240:243], v[42:45]
	v_mfma_f32_16x16x32_bf16 v[34:37], v[204:207], v[240:243], v[34:37]
	v_mfma_f32_16x16x32_bf16 v[10:13], v[208:211], v[240:243], v[10:13]
	v_mfma_f32_16x16x32_bf16 v[6:9], v[212:215], v[240:243], v[6:9]
	v_mfma_f32_16x16x32_bf16 v[46:49], v[200:203], v[244:247], v[46:49]
	v_mfma_f32_16x16x32_bf16 v[38:41], v[204:207], v[244:247], v[38:41]
	v_mfma_f32_16x16x32_bf16 v[14:17], v[208:211], v[244:247], v[14:17]
	v_mfma_f32_16x16x32_bf16 v[2:5], v[212:215], v[244:247], v[2:5]
	s_andn2_b64 vcc, exec, s[48:49]
	s_cbranch_vccz .Lattn2_adv
